# first-arriving workgroup of each XCD starts an un-waited L2 write-back at the grid barrier, on top of the combined version
# baseline (speedup 1.0000x reference)
.Lgb_nofirst:
	v_add_u32_e32 v3, v5, v3
	v_cmp_ne_u32_e32 vcc, v4, v3
	s_and_saveexec_b64 s[2:3], vcc
	s_xor_b64 s[2:3], exec, s[2:3]
	s_cbranch_execz .LBB0_1195
	v_readlane_b32 s4, v252, 13
	v_readlane_b32 s5, v252, 14
	s_waitcnt lgkmcnt(0)
	s_nop 3
	global_load_dword v2, v1, s[4:5] sc1
	s_waitcnt vmcnt(0)
	v_cmp_eq_u32_e32 vcc, v2, v0
	s_and_saveexec_b64 s[4:5], vcc
	s_cbranch_execz .LBB0_1194
	s_mov_b32 s16, 1
	s_mov_b64 s[6:7], 0
	s_branch .LBB0_1185
